# v16 + nt on SGU U-tile loads (lines are rewritten in place)
# baseline (speedup 1.0000x reference)
.LBB0_623:
	s_or_b64 exec, exec, s[36:37]
	v_mov_b32_e32 v3, v56
	s_waitcnt lgkmcnt(0)
	s_barrier
	v_readlane_b32 s2, v252, 44
	v_lshlrev_b32_e32 v5, 4, v3
	v_lshlrev_b32_e32 v2, 8, v3
	v_and_b32_e32 v4, 0x1f0, v5
	s_movk_i32 s1, 0xe000
	s_waitcnt vmcnt(0)
	v_readlane_b32 s3, v252, 45
	v_and_or_b32 v129, v2, s1, v4
	s_nop 4
	global_load_dwordx4 v[18:21], v129, s[2:3] nt
	v_readlane_b32 s2, v252, 32
	v_readlane_b32 s3, v252, 33
	s_nop 4
	global_load_dwordx4 v[22:25], v129, s[2:3] nt
	v_readlane_b32 s2, v252, 34
	v_readlane_b32 s3, v252, 35
	s_nop 4
	global_load_dwordx4 v[26:29], v129, s[2:3] nt
	v_readlane_b32 s2, v252, 36
	v_readlane_b32 s3, v252, 37
	s_nop 4
	global_load_dwordx4 v[30:33], v129, s[2:3] nt
	v_readlane_b32 s2, v252, 38
	v_readlane_b32 s3, v252, 39
	s_nop 4
	global_load_dwordx4 v[34:37], v129, s[2:3] nt
	v_readlane_b32 s2, v252, 40
	v_readlane_b32 s3, v252, 41
	s_nop 4
	global_load_dwordx4 v[38:41], v129, s[2:3] nt
	v_readlane_b32 s2, v252, 42
	v_readfirstlane_b32 s0, v3
	v_readlane_b32 s3, v252, 43
	s_ashr_i32 s0, s0, 6
	s_nop 4
	global_load_dwordx4 v[42:45], v129, s[2:3] nt
	v_readlane_b32 s2, v252, 46
	v_bfe_u32 v128, v3, 2, 4
	s_lshl_b32 s4, s0, 5
	v_lshlrev_b32_e32 v7, 3, v3
	v_readlane_b32 s3, v252, 47
	v_lshl_add_u32 v6, v128, 12, s4
	v_and_b32_e32 v2, 24, v7
	s_nop 4
	global_load_dwordx4 v[46:49], v129, s[2:3] nt
	v_readlane_b32 s2, v252, 48
	v_or_b32_e32 v8, v6, v2
	v_and_b32_e32 v6, 0x7f, v3
	v_readlane_b32 s3, v252, 49
	v_lshlrev_b32_e32 v131, 3, v6
	s_nop 4
	global_load_dwordx2 v[118:119], v131, s[2:3]
	v_readlane_b32 s2, v252, 62
	v_readlane_b32 s3, v252, 63
	v_lshlrev_b32_e32 v130, 1, v8
	s_nop 4
	global_load_dwordx4 v[78:81], v130, s[2:3] nt
	v_readlane_b32 s2, v252, 50
	v_readlane_b32 s3, v252, 51
	s_nop 4
	global_load_dwordx4 v[74:77], v130, s[2:3] nt
	v_readlane_b32 s2, v252, 52
	v_readlane_b32 s3, v252, 53
	s_nop 4
	global_load_dwordx4 v[70:73], v130, s[2:3] nt
	v_readlane_b32 s2, v252, 54
	v_readlane_b32 s3, v252, 55
	s_nop 4
	global_load_dwordx4 v[66:69], v130, s[2:3] nt
	v_readlane_b32 s2, v252, 56
	v_readlane_b32 s3, v252, 57
	s_nop 4
	global_load_dwordx4 v[62:65], v130, s[2:3] nt
	v_readlane_b32 s2, v252, 58
	v_readlane_b32 s3, v252, 59
	s_nop 4
	global_load_dwordx4 v[58:61], v130, s[2:3] nt
	v_readlane_b32 s2, v252, 60
	v_readlane_b32 s3, v252, 61
	s_nop 4
	global_load_dwordx4 v[54:57], v130, s[2:3] nt
	v_readlane_b32 s2, v253, 0
	v_readlane_b32 s3, v253, 1
	s_nop 4
	global_load_dwordx4 v[50:53], v130, s[2:3] nt
	s_waitcnt vmcnt(8)
	s_and_b64 vcc, exec, s[72:73]
	s_cbranch_vccz .LBB0_633
	v_readlane_b32 s5, v254, 58
	s_lshl_b32 s1, s5, 19
	v_readlane_b32 s2, v252, 30
	v_readlane_b32 s3, v252, 31
	s_add_u32 s2, s2, s1
	s_addc_u32 s3, s3, 0
	s_lshl_b32 s86, s5, 12
	v_readlane_b32 s16, v251, 14
	s_lshl_b64 s[6:7], s[86:87], 2
	v_readlane_b32 s24, v251, 22
	v_readlane_b32 s25, v251, 23
	s_add_u32 s10, s24, s6
	s_addc_u32 s11, s25, s7
	s_lshl_b32 s86, s5, 11
	v_readlane_b32 s30, v251, 28
	s_lshl_b64 s[8:9], s[86:87], 2
	v_readlane_b32 s31, v251, 29
	s_add_u32 s8, s30, s8
	v_and_b32_e32 v8, 63, v3
	v_readlane_b32 s26, v251, 24
	s_addc_u32 s9, s31, s9
	v_readlane_b32 s27, v251, 25
	s_add_u32 s6, s26, s6
	v_lshrrev_b32_e32 v13, 5, v8
	v_ashrrev_i32_e32 v8, 4, v3
	s_addc_u32 s7, s27, s7
	s_mulk_i32 s0, 0x2400
	v_ashrrev_i32_e32 v9, 31, v8
	s_ashr_i32 s5, s4, 31
	s_add_i32 s14, s0, 0
	v_lshlrev_b64 v[10:11], 8, v[8:9]
	s_lshl_b64 s[0:1], s[4:5], 2
	v_lshl_add_u64 v[10:11], s[2:3], 0, v[10:11]
	v_and_b32_e32 v7, 0x78, v7
	s_add_u32 s2, s10, s0
	v_lshlrev_b32_e32 v202, 1, v7
	s_addc_u32 s3, s11, s1
	v_and_b32_e32 v12, 31, v3
	v_lshl_add_u64 v[120:121], v[10:11], 0, v[202:203]
	v_lshlrev_b32_e32 v202, 2, v6
	s_add_u32 s0, s6, s0
	v_lshl_add_u64 v[122:123], s[8:9], 0, v[202:203]
	v_lshlrev_b32_e32 v202, 2, v12
	s_addc_u32 s1, s7, s1
	v_lshl_add_u64 v[126:127], s[0:1], 0, v[202:203]
	s_movk_i32 s1, 0x80
	v_lshl_add_u64 v[124:125], s[2:3], 0, v[202:203]
	v_cmp_gt_i32_e64 s[2:3], s1, v3
	s_lshl_b32 s1, s4, 2
	v_readlane_b32 s7, v254, 55
	s_add_i32 s1, s7, s1
	v_and_b32_e32 v5, 0xf0, v5
	s_add_i32 s0, 0, 0x12000
	v_readlane_b32 s6, v254, 54
	v_add_u32_e32 v133, s1, v202
	v_readlane_b32 s1, v254, 56
	v_lshlrev_b32_e32 v7, 4, v13
	v_add_u32_e32 v14, 0x200, v3
	v_add_u32_e32 v16, 0x400, v3
	v_add_u32_e32 v82, 0x600, v3
	v_add_u32_e32 v5, s0, v5
	v_lshl_add_u32 v132, v3, 2, s6
	v_lshl_add_u32 v134, v3, 3, s1
	v_add_u32_e32 v9, s0, v7
	s_movk_i32 s0, 0x110
	v_lshrrev_b32_e32 v15, 4, v14
	v_lshrrev_b32_e32 v17, 4, v16
	v_lshrrev_b32_e32 v83, 4, v82
	v_ashrrev_i32_e32 v84, 5, v3
	v_add_u32_e32 v85, 0x800, v3
	v_add_u32_e32 v86, 0xa00, v3
	v_add_u32_e32 v87, 0xc00, v3
	v_add_u32_e32 v3, 0xe00, v3
	v_or_b32_e32 v6, s4, v12
	v_mul_lo_u32 v8, v8, s0
	v_mul_lo_u32 v15, v15, s0
	v_mul_lo_u32 v17, v17, s0
	v_mul_lo_u32 v83, v83, s0
	s_movk_i32 s0, 0x210
	v_ashrrev_i32_e32 v14, 5, v14
	v_ashrrev_i32_e32 v16, 5, v16
	v_ashrrev_i32_e32 v82, 5, v82
	v_ashrrev_i32_e32 v85, 5, v85
	v_ashrrev_i32_e32 v86, 5, v86
	v_ashrrev_i32_e32 v87, 5, v87
	v_ashrrev_i32_e32 v3, 5, v3
	v_lshl_add_u32 v136, v13, 6, s1
	v_mul_u32_u24_e32 v88, 0x1080, v13
	v_lshl_or_b32 v89, v13, 3, 1
	v_mov_b32_e32 v91, 0xc60
	v_mov_b32_e32 v92, 0x2940
	v_mov_b32_e32 v93, 0x4620
	v_mov_b32_e32 v94, 0x6300
	v_mul_u32_u24_e32 v95, 0x240, v13
	v_lshl_or_b32 v13, v13, 2, 1
	v_readlane_b32 s17, v251, 15
	v_readlane_b32 s18, v251, 16
	v_add_u32_e32 v4, 0, v4
	v_lshl_add_u32 v135, v6, 2, s7
	v_lshl_add_u32 v6, v6, 1, 0
	v_add_u32_e32 v10, s14, v202
	v_lshl_add_u32 v11, v2, 2, s14
	v_mul_lo_u32 v84, v84, s0
	v_mul_lo_u32 v14, v14, s0
	v_mul_lo_u32 v16, v16, s0
	v_mul_lo_u32 v82, v82, s0
	v_mul_lo_u32 v85, v85, s0
	v_mul_lo_u32 v86, v86, s0
	v_mul_lo_u32 v87, v87, s0
	v_mul_lo_u32 v3, v3, s0
	v_mul_u32_u24_e32 v90, 0x210, v89
	v_mad_u32_u24 v91, v89, s0, v91
	v_mad_u32_u24 v92, v89, s0, v92
	v_mad_u32_u24 v93, v89, s0, v93
	v_mad_u32_u24 v89, v89, s0, v94
	v_mul_u32_u24_e32 v94, 0x90, v128
	v_mul_u32_u24_e32 v12, 0x110, v12
	v_lshlrev_b32_e32 v96, 2, v13
	v_mul_u32_u24_e32 v13, 0x90, v13
	v_or_b32_e32 v97, 8, v7
	v_or_b32_e32 v98, 12, v7
	v_or_b32_e32 v99, 32, v7
	v_or_b32_e32 v100, 36, v7
	v_or_b32_e32 v101, 40, v7
	v_or_b32_e32 v102, 44, v7
	v_or_b32_e32 v103, 64, v7
	v_or_b32_e32 v104, 0x44, v7
	v_or_b32_e32 v105, 0x48, v7
	v_or_b32_e32 v106, 0x4c, v7
	v_or_b32_e32 v107, 0x60, v7
	v_or_b32_e32 v108, 0x64, v7
	v_or_b32_e32 v109, 0x68, v7
	v_or_b32_e32 v110, 0x6c, v7
	v_or_b32_e32 v111, 0x80, v7
	v_or_b32_e32 v112, 0x84, v7
	v_or_b32_e32 v113, 0x88, v7
	v_or_b32_e32 v114, 0x8c, v7
	v_or_b32_e32 v115, 0xa0, v7
	v_or_b32_e32 v116, 0xa4, v7
	v_or_b32_e32 v117, 0xa8, v7
	v_or_b32_e32 v202, 0xac, v7
	v_or_b32_e32 v204, 0xc0, v7
	v_or_b32_e32 v205, 0xc4, v7
	v_or_b32_e32 v206, 0xc8, v7
	v_or_b32_e32 v207, 0xcc, v7
	v_or_b32_e32 v223, 0xe0, v7
	v_or_b32_e32 v224, 0xe4, v7
	v_or_b32_e32 v225, 0xe8, v7
	v_or_b32_e32 v226, 0xec, v7
	v_readlane_b32 s0, v254, 57
	v_add_u32_e32 v137, 0x180, v136
	v_add_u32_e32 v138, 0x190, v136
	v_add_u32_e32 v139, 0x1a0, v136
	v_add_u32_e32 v140, 0x1b0, v136
	v_add_u32_e32 v141, 0x200, v136
	v_add_u32_e32 v142, 0x210, v136
	v_add_u32_e32 v143, 0x220, v136
	v_add_u32_e32 v144, 0x230, v136
	v_add_u32_e32 v145, 0x280, v136
	v_add_u32_e32 v146, 0x290, v136
	v_add_u32_e32 v147, 0x2a0, v136
	v_add_u32_e32 v148, 0x2b0, v136
	v_add_u32_e32 v149, 0x300, v136
	v_add_u32_e32 v150, 0x310, v136
	v_add_u32_e32 v151, 0x320, v136
	v_add_u32_e32 v152, 0x330, v136
	v_add_u32_e32 v153, 0x380, v136
	v_add_u32_e32 v154, 0x390, v136
	v_add_u32_e32 v155, 0x3a0, v136
	v_add_u32_e32 v156, 0x3b0, v136
	v_add_u32_e32 v157, s6, v7
	v_add_u32_e32 v158, s6, v96
	v_add_u32_e32 v159, s6, v97
	v_add_u32_e32 v160, s6, v98
	v_add_u32_e32 v161, s6, v99
	v_add_u32_e32 v162, s6, v100
	v_add_u32_e32 v163, s6, v101
	v_add_u32_e32 v164, s6, v102
	v_add_u32_e32 v165, s6, v103
	v_add_u32_e32 v166, s6, v104
	v_add_u32_e32 v167, s6, v105
	v_add_u32_e32 v168, s6, v106
	v_add_u32_e32 v169, s6, v107
	v_add_u32_e32 v170, s6, v108
	v_add_u32_e32 v171, s6, v109
	v_add_u32_e32 v172, s6, v110
	v_add_u32_e32 v173, s6, v111
	v_add_u32_e32 v174, s6, v112
	v_add_u32_e32 v175, s6, v113
	v_add_u32_e32 v176, s6, v114
	v_add_u32_e32 v177, s6, v115
	v_add_u32_e32 v178, s6, v116
	v_add_u32_e32 v179, s6, v117
	v_add_u32_e32 v180, s6, v202
	v_add_u32_e32 v181, s6, v204
	v_add_u32_e32 v182, s6, v205
	v_add_u32_e32 v183, s6, v206
	v_add_u32_e32 v184, s6, v207
	v_add_u32_e32 v185, s6, v223
	v_add_u32_e32 v186, s6, v224
	v_add_u32_e32 v187, s6, v225
	v_add_u32_e32 v188, s6, v226
	v_add_u32_e32 v189, s0, v7
	v_add_u32_e32 v190, s0, v96
	v_add_u32_e32 v191, s0, v97
	v_add_u32_e32 v192, s0, v98
	v_add_u32_e32 v193, s0, v99
	v_add_u32_e32 v194, s0, v100
	v_add_u32_e32 v195, s0, v101
	v_add_u32_e32 v196, s0, v102
	v_add_u32_e32 v197, s0, v103
	v_add_u32_e32 v198, s0, v104
	v_add_u32_e32 v199, s0, v105
	v_add_u32_e32 v200, s0, v106
	v_add_u32_e32 v201, s0, v107
	v_add_u32_e32 v208, s0, v108
	v_add_u32_e32 v209, s0, v109
	v_add_u32_e32 v210, s0, v110
	v_add_u32_e32 v211, s0, v111
	v_add_u32_e32 v212, s0, v112
	v_add_u32_e32 v213, s0, v113
	v_add_u32_e32 v214, s0, v114
	v_add_u32_e32 v215, s0, v115
	v_add_u32_e32 v216, s0, v116
	v_add_u32_e32 v217, s0, v117
	v_add_u32_e32 v218, s0, v202
	v_add_u32_e32 v219, s0, v204
	v_add_u32_e32 v220, s0, v205
	v_add_u32_e32 v221, s0, v206
	v_add_u32_e32 v222, s0, v207
	v_add_u32_e32 v223, s0, v223
	v_add_u32_e32 v224, s0, v224
	v_add_u32_e32 v225, s0, v225
	v_add_u32_e32 v226, s0, v226
	s_lshl_b32 s14, s96, 8
	s_lshl_b32 s15, s96, 7
	s_mov_b32 s18, -1
	v_add_u32_e32 v227, v5, v8
	v_add_u32_e32 v228, v5, v15
	v_add_u32_e32 v229, v5, v17
	v_add_u32_e32 v230, v5, v83
	v_add_u32_e32 v231, v4, v84
	v_add_u32_e32 v232, v4, v14
	v_add_u32_e32 v233, v4, v16
	v_add_u32_e32 v238, v4, v82
	v_add_u32_e32 v239, v4, v85
	v_add_u32_e32 v240, v4, v86
	v_add_u32_e32 v241, v4, v87
	v_add_u32_e32 v242, v4, v3
	v_add_u32_e32 v243, v6, v88
	v_add_u32_e32 v244, v6, v90
	v_add_u32_e32 v245, v6, v91
	v_add_u32_e32 v246, v6, v92
	v_add_u32_e32 v247, v6, v93
	v_add_u32_e32 v248, v6, v89
	v_lshlrev_b32_e32 v202, 1, v2
	v_add_u32_e32 v249, v9, v12
	v_add_u32_e32 v250, v10, v95
	v_add_u32_e32 v204, v10, v13
	v_add_u32_e32 v205, v11, v94
	v_readlane_b32 s16, v254, 31
	v_readlane_b32 s17, v254, 30
	s_mov_b32 s10, s84
	s_mov_b32 s57, 0x20000
	s_mov_b32 s88, 0x40000
	v_readlane_b32 s19, v251, 17
	v_readlane_b32 s20, v251, 18
	v_readlane_b32 s21, v251, 19
	v_readlane_b32 s22, v251, 20
	v_readlane_b32 s23, v251, 21
	v_readlane_b32 s28, v251, 26
	v_readlane_b32 s29, v251, 27

.LBB0_629:
	s_and_saveexec_b64 s[6:7], s[2:3]
	ds_write_b64 v134, v[118:119]
	s_or_b64 exec, exec, s[6:7]
	s_add_i32 s19, s10, s96
	s_cmpk_lt_i32 s19, 0x840
	s_cselect_b64 s[6:7], -1, 0
	s_and_b64 s[0:1], s[6:7], exec
	s_cselect_b32 s0, s19, s10
	s_ashr_i32 s1, s0, 31
	s_lshr_b32 s1, s1, 28
	s_add_i32 s1, s0, s1
	s_and_b32 s8, s1, 0xfffff0
	s_sub_i32 s10, s0, s8
	s_lshl_b32 s0, s1, 3
	s_and_b32 s0, s0, 0xffffff80
	s_ashr_i32 s1, s0, 31
	s_lshl_b64 s[8:9], s[0:1], 13
	v_readlane_b32 s22, v252, 0
	v_readlane_b32 s23, v252, 1
	s_add_u32 s21, s22, s8
	s_addc_u32 s23, s23, s9
	s_lshl_b32 s10, s10, 8
	s_ashr_i32 s11, s10, 31
	s_lshl_b64 s[10:11], s[10:11], 1
	s_add_u32 s22, s21, s10
	s_addc_u32 s23, s23, s11
	s_add_u32 s24, s22, 0x20000
	ds_write_b128 v231, v[18:21]
	ds_write_b128 v232, v[22:25]
	ds_write_b128 v233, v[26:29]
	ds_write_b128 v238, v[30:33]
	ds_write_b128 v239, v[34:37]
	ds_write_b128 v240, v[38:41]
	ds_write_b128 v241, v[42:45]
	ds_write_b128 v242, v[46:49]
	s_waitcnt lgkmcnt(0)
	s_barrier
	s_nop 4
	global_load_dwordx4 v[18:21], v129, s[22:23] nt
	s_addc_u32 s25, s23, 0
	s_nop 4
	global_load_dwordx4 v[22:25], v129, s[24:25] nt
	s_add_u32 s24, s22, 0x40000
	s_addc_u32 s25, s23, 0
	s_nop 4
	global_load_dwordx4 v[26:29], v129, s[24:25] nt
	s_add_u32 s24, s22, 0x60000
	s_addc_u32 s25, s23, 0
	s_nop 4
	global_load_dwordx4 v[30:33], v129, s[24:25] nt
	s_add_u32 s24, s22, 0x80000
	s_addc_u32 s25, s23, 0
	s_nop 4
	global_load_dwordx4 v[34:37], v129, s[24:25] nt
	s_add_u32 s24, s22, 0xa0000
	s_addc_u32 s25, s23, 0
	s_nop 4
	global_load_dwordx4 v[38:41], v129, s[24:25] nt
	s_add_u32 s24, s22, 0xc0000
	s_addc_u32 s25, s23, 0
	s_add_u32 s22, s22, 0xe0000
	s_nop 4
	global_load_dwordx4 v[42:45], v129, s[24:25] nt
	s_addc_u32 s23, s23, 0
	s_lshl_b64 s[0:1], s[0:1], 3
	s_nop 4
	global_load_dwordx4 v[46:49], v129, s[22:23] nt
	s_add_u32 s0, s12, s0
	s_addc_u32 s1, s83, s1
	s_nop 4
	global_load_dwordx2 v[118:119], v131, s[0:1]
	v_add_u32_e32 v6, 16, v136
	ds_read_b32 v110, v135
	ds_read_b32 v112, v133 offset:1024
	ds_read_b128 v[2:5], v136
	ds_read_u16 v82, v243
	ds_read_u16 v86, v244
	ds_read_b128 v[6:9], v6
	ds_read_u16 v83, v244 offset:528
	ds_read_u16 v87, v244 offset:1056
	v_add_u32_e32 v10, 32, v136
	v_add_u32_e32 v14, 48, v136
	ds_read_b128 v[10:13], v10
	ds_read_u16 v88, v244 offset:1584
	ds_read_u16 v89, v244 offset:2112
	ds_read_b128 v[14:17], v14
	ds_read_u16 v90, v244 offset:2640
	ds_read_u16 v91, v245
	s_waitcnt lgkmcnt(0)
	v_lshlrev_b32_e32 v83, 16, v83
	v_lshlrev_b32_e32 v82, 16, v82
	v_mov_b32_e32 v84, v2
	v_mov_b32_e32 v85, v6
	v_pk_add_f32 v[82:83], v[82:83], v[84:85] neg_lo:[0,1] neg_hi:[0,1]
	v_mov_b32_e32 v6, v3
	v_pk_mul_f32 v[2:3], v[6:7], v[82:83]
	v_lshlrev_b32_e32 v7, 16, v87
	v_lshlrev_b32_e32 v6, 16, v86
	v_mov_b32_e32 v82, v4
	v_mov_b32_e32 v83, v8
	v_pk_add_f32 v[6:7], v[6:7], v[82:83] neg_lo:[0,1] neg_hi:[0,1]
	v_mov_b32_e32 v8, v5
	v_pk_mul_f32 v[4:5], v[8:9], v[6:7]
	v_lshlrev_b32_e32 v7, 16, v90
	v_lshlrev_b32_e32 v6, 16, v88
	v_mov_b32_e32 v8, v10
	v_mov_b32_e32 v9, v14
	v_pk_add_f32 v[6:7], v[6:7], v[8:9] neg_lo:[0,1] neg_hi:[0,1]
	v_mov_b32_e32 v14, v11
	v_lshlrev_b32_e32 v9, 16, v91
	v_lshlrev_b32_e32 v8, 16, v89
	v_mov_b32_e32 v10, v12
	v_mov_b32_e32 v11, v16
	v_pk_add_f32 v[8:9], v[8:9], v[10:11] neg_lo:[0,1] neg_hi:[0,1]
	v_mov_b32_e32 v16, v13
	v_pk_mul_f32 v[8:9], v[16:17], v[8:9]
	v_pk_fma_f32 v[4:5], v[110:111], v[4:5], v[112:113] op_sel_hi:[0,1,0]
	v_pk_mul_f32 v[6:7], v[14:15], v[6:7]
	v_pk_fma_f32 v[8:9], v[110:111], v[8:9], v[112:113] op_sel_hi:[0,1,0]
	v_pk_fma_f32 v[2:3], v[110:111], v[2:3], v[112:113] op_sel_hi:[0,1,0]
	v_pk_fma_f32 v[6:7], v[110:111], v[6:7], v[112:113] op_sel_hi:[0,1,0]
	v_bfe_u32 v10, v9, 16, 1
	v_bfe_u32 v12, v5, 16, 1
	v_bfe_u32 v11, v8, 16, 1
	v_bfe_u32 v13, v4, 16, 1
	v_add3_u32 v5, v5, v12, s53
	v_add3_u32 v9, v9, v10, s53
	v_bfe_u32 v10, v2, 16, 1
	v_bfe_u32 v12, v6, 16, 1
	v_add3_u32 v4, v4, v13, s53
	v_add3_u32 v8, v8, v11, s53
	v_bfe_u32 v11, v3, 16, 1
	v_bfe_u32 v13, v7, 16, 1
	v_add3_u32 v6, v6, v12, s53
	v_add3_u32 v2, v2, v10, s53
	v_add3_u32 v7, v7, v13, s53
	v_add3_u32 v3, v3, v11, s53
	v_lshrrev_b32_e32 v2, 16, v2
	v_lshrrev_b32_e32 v6, 16, v6
	v_lshrrev_b32_e32 v3, 16, v3
	v_lshrrev_b32_e32 v7, 16, v7
	v_and_or_b32 v84, v8, s77, v6
	v_and_or_b32 v82, v4, s77, v2
	v_add_u32_e32 v2, 0x80, v136
	v_add_u32_e32 v6, 0x90, v136
	v_and_or_b32 v85, v9, s77, v7
	v_and_or_b32 v83, v5, s77, v3
	ds_read_b128 v[2:5], v2
	ds_read_u16 v86, v245 offset:4752
	ds_read_u16 v90, v245 offset:5280
	ds_read_b128 v[6:9], v6
	ds_read_u16 v87, v245 offset:5808
	ds_read_u16 v91, v245 offset:6336
	v_add_u32_e32 v10, 0xa0, v136
	v_add_u32_e32 v14, 0xb0, v136
	ds_read_b128 v[10:13], v10
	ds_read_u16 v92, v245 offset:6864
	ds_read_u16 v93, v246
	ds_read_b128 v[14:17], v14
	ds_read_u16 v94, v246 offset:528
	ds_read_u16 v95, v246 offset:1056
	s_waitcnt lgkmcnt(0)
	v_lshlrev_b32_e32 v87, 16, v87
	v_lshlrev_b32_e32 v86, 16, v86
	v_mov_b32_e32 v88, v2
	v_mov_b32_e32 v89, v6
	v_pk_add_f32 v[86:87], v[86:87], v[88:89] neg_lo:[0,1] neg_hi:[0,1]
	v_mov_b32_e32 v6, v3
	v_pk_mul_f32 v[2:3], v[6:7], v[86:87]
	v_lshlrev_b32_e32 v7, 16, v91
	v_lshlrev_b32_e32 v6, 16, v90
	v_mov_b32_e32 v86, v4
	v_mov_b32_e32 v87, v8
	v_pk_add_f32 v[6:7], v[6:7], v[86:87] neg_lo:[0,1] neg_hi:[0,1]
	v_mov_b32_e32 v8, v5
	v_pk_mul_f32 v[4:5], v[8:9], v[6:7]
	v_lshlrev_b32_e32 v7, 16, v94
	v_lshlrev_b32_e32 v6, 16, v92
	v_mov_b32_e32 v8, v10
	v_mov_b32_e32 v9, v14
	v_pk_add_f32 v[6:7], v[6:7], v[8:9] neg_lo:[0,1] neg_hi:[0,1]
	v_mov_b32_e32 v14, v11
	v_lshlrev_b32_e32 v9, 16, v95
	v_lshlrev_b32_e32 v8, 16, v93
	v_mov_b32_e32 v10, v12
	v_mov_b32_e32 v11, v16
	v_pk_add_f32 v[8:9], v[8:9], v[10:11] neg_lo:[0,1] neg_hi:[0,1]
	v_mov_b32_e32 v16, v13
	v_pk_mul_f32 v[8:9], v[16:17], v[8:9]
	v_pk_fma_f32 v[4:5], v[110:111], v[4:5], v[112:113] op_sel_hi:[0,1,0]
	v_pk_mul_f32 v[6:7], v[14:15], v[6:7]
	v_pk_fma_f32 v[8:9], v[110:111], v[8:9], v[112:113] op_sel_hi:[0,1,0]
	v_pk_fma_f32 v[2:3], v[110:111], v[2:3], v[112:113] op_sel_hi:[0,1,0]
	v_pk_fma_f32 v[6:7], v[110:111], v[6:7], v[112:113] op_sel_hi:[0,1,0]
	v_bfe_u32 v10, v9, 16, 1
	v_bfe_u32 v12, v5, 16, 1
	v_bfe_u32 v11, v8, 16, 1
	v_bfe_u32 v13, v4, 16, 1
	v_add3_u32 v5, v5, v12, s53
	v_add3_u32 v9, v9, v10, s53
	v_bfe_u32 v10, v2, 16, 1
	v_bfe_u32 v12, v6, 16, 1
	v_add3_u32 v4, v4, v13, s53
	v_add3_u32 v8, v8, v11, s53
	v_bfe_u32 v11, v3, 16, 1
	v_bfe_u32 v13, v7, 16, 1
	v_add3_u32 v6, v6, v12, s53
	v_add3_u32 v2, v2, v10, s53
	v_add3_u32 v7, v7, v13, s53
	v_add3_u32 v3, v3, v11, s53
	v_lshrrev_b32_e32 v2, 16, v2
	v_lshrrev_b32_e32 v6, 16, v6
	v_lshrrev_b32_e32 v3, 16, v3
	v_lshrrev_b32_e32 v7, 16, v7
	v_and_or_b32 v88, v8, s77, v6
	v_and_or_b32 v86, v4, s77, v2
	v_add_u32_e32 v2, 0x100, v136
	v_add_u32_e32 v6, 0x110, v136
	v_and_or_b32 v89, v9, s77, v7
	v_and_or_b32 v87, v5, s77, v3
	ds_read_b128 v[2:5], v2
	ds_read_u16 v90, v246 offset:5808
	ds_read_u16 v94, v246 offset:6336
	ds_read_b128 v[6:9], v6
	ds_read_u16 v91, v246 offset:6864
	ds_read_u16 v95, v247
	v_add_u32_e32 v10, 0x120, v136
	v_add_u32_e32 v14, 0x130, v136
	ds_read_b128 v[10:13], v10
	ds_read_u16 v96, v247 offset:528
	ds_read_u16 v97, v247 offset:1056
	ds_read_b128 v[14:17], v14
	ds_read_u16 v98, v247 offset:1584
	ds_read_u16 v99, v247 offset:2112
	s_waitcnt lgkmcnt(0)
	v_lshlrev_b32_e32 v91, 16, v91
	v_lshlrev_b32_e32 v90, 16, v90
	v_mov_b32_e32 v92, v2
	v_mov_b32_e32 v93, v6
	v_pk_add_f32 v[90:91], v[90:91], v[92:93] neg_lo:[0,1] neg_hi:[0,1]
	v_mov_b32_e32 v6, v3
	v_pk_mul_f32 v[2:3], v[6:7], v[90:91]
	v_lshlrev_b32_e32 v7, 16, v95
	v_lshlrev_b32_e32 v6, 16, v94
	v_mov_b32_e32 v90, v4
	v_mov_b32_e32 v91, v8
	v_pk_add_f32 v[6:7], v[6:7], v[90:91] neg_lo:[0,1] neg_hi:[0,1]
	v_mov_b32_e32 v8, v5
	v_pk_mul_f32 v[4:5], v[8:9], v[6:7]
	v_lshlrev_b32_e32 v7, 16, v98
	v_lshlrev_b32_e32 v6, 16, v96
	v_mov_b32_e32 v8, v10
	v_mov_b32_e32 v9, v14
	v_pk_add_f32 v[6:7], v[6:7], v[8:9] neg_lo:[0,1] neg_hi:[0,1]
	v_mov_b32_e32 v14, v11
	v_lshlrev_b32_e32 v9, 16, v99
	v_lshlrev_b32_e32 v8, 16, v97
	v_mov_b32_e32 v10, v12
	v_mov_b32_e32 v11, v16
	v_pk_add_f32 v[8:9], v[8:9], v[10:11] neg_lo:[0,1] neg_hi:[0,1]
	v_mov_b32_e32 v16, v13
	v_pk_mul_f32 v[8:9], v[16:17], v[8:9]
	v_pk_fma_f32 v[4:5], v[110:111], v[4:5], v[112:113] op_sel_hi:[0,1,0]
	v_pk_mul_f32 v[6:7], v[14:15], v[6:7]
	v_pk_fma_f32 v[8:9], v[110:111], v[8:9], v[112:113] op_sel_hi:[0,1,0]
	v_pk_fma_f32 v[2:3], v[110:111], v[2:3], v[112:113] op_sel_hi:[0,1,0]
	v_pk_fma_f32 v[6:7], v[110:111], v[6:7], v[112:113] op_sel_hi:[0,1,0]
	v_bfe_u32 v10, v9, 16, 1
	v_bfe_u32 v11, v8, 16, 1
	v_bfe_u32 v12, v5, 16, 1
	v_bfe_u32 v13, v4, 16, 1
	v_add3_u32 v4, v4, v13, s53
	v_add3_u32 v5, v5, v12, s53
	v_add3_u32 v8, v8, v11, s53
	v_add3_u32 v9, v9, v10, s53
	v_bfe_u32 v10, v2, 16, 1
	v_bfe_u32 v11, v3, 16, 1
	v_bfe_u32 v12, v6, 16, 1
	v_bfe_u32 v13, v7, 16, 1
	v_add3_u32 v7, v7, v13, s53
	v_add3_u32 v6, v6, v12, s53
	v_add3_u32 v3, v3, v11, s53
	v_add3_u32 v2, v2, v10, s53
	v_lshrrev_b32_e32 v2, 16, v2
	v_lshrrev_b32_e32 v3, 16, v3
	v_lshrrev_b32_e32 v6, 16, v6
	v_lshrrev_b32_e32 v7, 16, v7
	v_and_or_b32 v93, v9, s77, v7
	v_and_or_b32 v92, v8, s77, v6
	v_and_or_b32 v91, v5, s77, v3
	v_and_or_b32 v90, v4, s77, v2
	ds_read_b128 v[2:5], v137
	ds_read_u16 v94, v247 offset:6864
	ds_read_u16 v98, v248
	ds_read_b128 v[6:9], v138
	ds_read_u16 v95, v248 offset:528
	ds_read_u16 v99, v248 offset:1056
	ds_read_b128 v[10:13], v139
	ds_read_u16 v100, v248 offset:1584
	ds_read_u16 v101, v248 offset:2112
	ds_read_b128 v[14:17], v140
	ds_read_u16 v102, v248 offset:2640
	ds_read_u16 v103, v248 offset:3168
	s_waitcnt lgkmcnt(0)
	v_lshlrev_b32_e32 v95, 16, v95
	v_lshlrev_b32_e32 v94, 16, v94
	v_mov_b32_e32 v96, v2
	v_mov_b32_e32 v97, v6
	v_pk_add_f32 v[94:95], v[94:95], v[96:97] neg_lo:[0,1] neg_hi:[0,1]
	v_mov_b32_e32 v6, v3
	v_pk_mul_f32 v[2:3], v[6:7], v[94:95]
	v_lshlrev_b32_e32 v7, 16, v99
	v_lshlrev_b32_e32 v6, 16, v98
	v_mov_b32_e32 v94, v4
	v_mov_b32_e32 v95, v8
	v_pk_add_f32 v[6:7], v[6:7], v[94:95] neg_lo:[0,1] neg_hi:[0,1]
	v_mov_b32_e32 v8, v5
	v_pk_mul_f32 v[4:5], v[8:9], v[6:7]
	v_lshlrev_b32_e32 v7, 16, v102
	v_lshlrev_b32_e32 v6, 16, v100
	v_mov_b32_e32 v8, v10
	v_mov_b32_e32 v9, v14
	v_pk_add_f32 v[6:7], v[6:7], v[8:9] neg_lo:[0,1] neg_hi:[0,1]
	v_mov_b32_e32 v14, v11
	v_lshlrev_b32_e32 v9, 16, v103
	v_lshlrev_b32_e32 v8, 16, v101
	v_mov_b32_e32 v10, v12
	v_mov_b32_e32 v11, v16
	v_pk_add_f32 v[8:9], v[8:9], v[10:11] neg_lo:[0,1] neg_hi:[0,1]
	v_mov_b32_e32 v16, v13
	v_pk_mul_f32 v[8:9], v[16:17], v[8:9]
	v_pk_fma_f32 v[4:5], v[110:111], v[4:5], v[112:113] op_sel_hi:[0,1,0]
	v_pk_mul_f32 v[6:7], v[14:15], v[6:7]
	v_pk_fma_f32 v[8:9], v[110:111], v[8:9], v[112:113] op_sel_hi:[0,1,0]
	v_pk_fma_f32 v[2:3], v[110:111], v[2:3], v[112:113] op_sel_hi:[0,1,0]
	v_pk_fma_f32 v[6:7], v[110:111], v[6:7], v[112:113] op_sel_hi:[0,1,0]
	v_bfe_u32 v10, v9, 16, 1
	v_bfe_u32 v11, v8, 16, 1
	v_bfe_u32 v12, v5, 16, 1
	v_bfe_u32 v13, v4, 16, 1
	v_add3_u32 v4, v4, v13, s53
	v_add3_u32 v5, v5, v12, s53
	v_add3_u32 v8, v8, v11, s53
	v_add3_u32 v9, v9, v10, s53
	v_bfe_u32 v10, v2, 16, 1
	v_bfe_u32 v11, v3, 16, 1
	v_bfe_u32 v12, v6, 16, 1
	v_bfe_u32 v13, v7, 16, 1
	v_add3_u32 v7, v7, v13, s53
	v_add3_u32 v6, v6, v12, s53
	v_add3_u32 v3, v3, v11, s53
	v_add3_u32 v2, v2, v10, s53
	v_lshrrev_b32_e32 v2, 16, v2
	v_lshrrev_b32_e32 v3, 16, v3
	v_lshrrev_b32_e32 v6, 16, v6
	v_lshrrev_b32_e32 v7, 16, v7
	v_and_or_b32 v97, v9, s77, v7
	v_and_or_b32 v96, v8, s77, v6
	v_and_or_b32 v95, v5, s77, v3
	v_and_or_b32 v94, v4, s77, v2
	ds_read_b128 v[2:5], v141
	ds_read_u16 v98, v248 offset:7920
	ds_read_u16 v102, v248 offset:8448
	ds_read_b128 v[6:9], v142
	ds_read_u16 v99, v248 offset:8976
	ds_read_u16 v103, v248 offset:9504
	ds_read_b128 v[10:13], v143
	ds_read_u16 v104, v248 offset:10032
	ds_read_u16 v105, v248 offset:10560
	ds_read_b128 v[14:17], v144
	ds_read_u16 v106, v248 offset:11088
	ds_read_u16 v107, v248 offset:11616
	s_waitcnt lgkmcnt(0)
	v_lshlrev_b32_e32 v99, 16, v99
	v_lshlrev_b32_e32 v98, 16, v98
	v_mov_b32_e32 v100, v2
	v_mov_b32_e32 v101, v6
	v_pk_add_f32 v[98:99], v[98:99], v[100:101] neg_lo:[0,1] neg_hi:[0,1]
	v_mov_b32_e32 v6, v3
	v_pk_mul_f32 v[2:3], v[6:7], v[98:99]
	v_lshlrev_b32_e32 v7, 16, v103
	v_lshlrev_b32_e32 v6, 16, v102
	v_mov_b32_e32 v98, v4
	v_mov_b32_e32 v99, v8
	v_pk_add_f32 v[6:7], v[6:7], v[98:99] neg_lo:[0,1] neg_hi:[0,1]
	v_mov_b32_e32 v8, v5
	v_pk_mul_f32 v[4:5], v[8:9], v[6:7]
	v_lshlrev_b32_e32 v7, 16, v106
	v_lshlrev_b32_e32 v6, 16, v104
	v_mov_b32_e32 v8, v10
	v_mov_b32_e32 v9, v14
	v_pk_add_f32 v[6:7], v[6:7], v[8:9] neg_lo:[0,1] neg_hi:[0,1]
	v_mov_b32_e32 v14, v11
	v_lshlrev_b32_e32 v9, 16, v107
	v_lshlrev_b32_e32 v8, 16, v105
	v_mov_b32_e32 v10, v12
	v_mov_b32_e32 v11, v16
	v_pk_add_f32 v[8:9], v[8:9], v[10:11] neg_lo:[0,1] neg_hi:[0,1]
	v_mov_b32_e32 v16, v13
	v_pk_mul_f32 v[8:9], v[16:17], v[8:9]
	v_pk_fma_f32 v[4:5], v[110:111], v[4:5], v[112:113] op_sel_hi:[0,1,0]
	v_pk_mul_f32 v[6:7], v[14:15], v[6:7]
	v_pk_fma_f32 v[8:9], v[110:111], v[8:9], v[112:113] op_sel_hi:[0,1,0]
	v_pk_fma_f32 v[2:3], v[110:111], v[2:3], v[112:113] op_sel_hi:[0,1,0]
	v_pk_fma_f32 v[6:7], v[110:111], v[6:7], v[112:113] op_sel_hi:[0,1,0]
	v_bfe_u32 v10, v9, 16, 1
	v_bfe_u32 v11, v8, 16, 1
	v_bfe_u32 v12, v5, 16, 1
	v_bfe_u32 v13, v4, 16, 1
	v_add3_u32 v4, v4, v13, s53
	v_add3_u32 v5, v5, v12, s53
	v_add3_u32 v8, v8, v11, s53
	v_add3_u32 v9, v9, v10, s53
	v_bfe_u32 v10, v2, 16, 1
	v_bfe_u32 v11, v3, 16, 1
	v_bfe_u32 v12, v6, 16, 1
	v_bfe_u32 v13, v7, 16, 1
	v_add3_u32 v7, v7, v13, s53
	v_add3_u32 v6, v6, v12, s53
	v_add3_u32 v3, v3, v11, s53
	v_add3_u32 v2, v2, v10, s53
	v_lshrrev_b32_e32 v2, 16, v2
	v_lshrrev_b32_e32 v3, 16, v3
	v_lshrrev_b32_e32 v6, 16, v6
	v_lshrrev_b32_e32 v7, 16, v7
	v_and_or_b32 v101, v9, s77, v7
	v_and_or_b32 v100, v8, s77, v6
	v_and_or_b32 v99, v5, s77, v3
	v_and_or_b32 v98, v4, s77, v2
	ds_read_b128 v[2:5], v145
	ds_read_u16 v102, v248 offset:16368
	ds_read_u16 v106, v248 offset:16896
	ds_read_b128 v[6:9], v146
	ds_read_u16 v103, v248 offset:17424
	ds_read_u16 v107, v248 offset:17952
	ds_read_b128 v[10:13], v147
	ds_read_u16 v108, v248 offset:18480
	ds_read_u16 v109, v248 offset:19008
	ds_read_b128 v[14:17], v148
	ds_read_u16 v111, v248 offset:19536
	ds_read_u16 v113, v248 offset:20064
	s_waitcnt lgkmcnt(0)
	v_lshlrev_b32_e32 v103, 16, v103
	v_lshlrev_b32_e32 v102, 16, v102
	v_mov_b32_e32 v104, v2
	v_mov_b32_e32 v105, v6
	v_pk_add_f32 v[102:103], v[102:103], v[104:105] neg_lo:[0,1] neg_hi:[0,1]
	v_mov_b32_e32 v6, v3
	v_pk_mul_f32 v[2:3], v[6:7], v[102:103]
	v_lshlrev_b32_e32 v7, 16, v107
	v_lshlrev_b32_e32 v6, 16, v106
	v_mov_b32_e32 v102, v4
	v_mov_b32_e32 v103, v8
	v_pk_add_f32 v[6:7], v[6:7], v[102:103] neg_lo:[0,1] neg_hi:[0,1]
	v_mov_b32_e32 v8, v5
	v_pk_mul_f32 v[4:5], v[8:9], v[6:7]
	v_lshlrev_b32_e32 v7, 16, v111
	v_lshlrev_b32_e32 v6, 16, v108
	v_mov_b32_e32 v8, v10
	v_mov_b32_e32 v9, v14
	v_pk_add_f32 v[6:7], v[6:7], v[8:9] neg_lo:[0,1] neg_hi:[0,1]
	v_mov_b32_e32 v14, v11
	v_lshlrev_b32_e32 v9, 16, v113
	v_lshlrev_b32_e32 v8, 16, v109
	v_mov_b32_e32 v10, v12
	v_mov_b32_e32 v11, v16
	v_pk_add_f32 v[8:9], v[8:9], v[10:11] neg_lo:[0,1] neg_hi:[0,1]
	v_mov_b32_e32 v16, v13
	v_pk_mul_f32 v[8:9], v[16:17], v[8:9]
	v_pk_fma_f32 v[4:5], v[110:111], v[4:5], v[112:113] op_sel_hi:[0,1,0]
	v_pk_mul_f32 v[6:7], v[14:15], v[6:7]
	v_pk_fma_f32 v[8:9], v[110:111], v[8:9], v[112:113] op_sel_hi:[0,1,0]
	v_pk_fma_f32 v[2:3], v[110:111], v[2:3], v[112:113] op_sel_hi:[0,1,0]
	v_pk_fma_f32 v[6:7], v[110:111], v[6:7], v[112:113] op_sel_hi:[0,1,0]
	v_bfe_u32 v10, v9, 16, 1
	v_bfe_u32 v11, v8, 16, 1
	v_bfe_u32 v12, v5, 16, 1
	v_bfe_u32 v13, v4, 16, 1
	v_add3_u32 v4, v4, v13, s53
	v_add3_u32 v5, v5, v12, s53
	v_add3_u32 v8, v8, v11, s53
	v_add3_u32 v9, v9, v10, s53
	v_bfe_u32 v10, v2, 16, 1
	v_bfe_u32 v11, v3, 16, 1
	v_bfe_u32 v12, v6, 16, 1
	v_bfe_u32 v13, v7, 16, 1
	v_add3_u32 v7, v7, v13, s53
	v_add3_u32 v6, v6, v12, s53
	v_add3_u32 v3, v3, v11, s53
	v_add3_u32 v2, v2, v10, s53
	v_lshrrev_b32_e32 v2, 16, v2
	v_lshrrev_b32_e32 v3, 16, v3
	v_lshrrev_b32_e32 v6, 16, v6
	v_lshrrev_b32_e32 v7, 16, v7
	v_and_or_b32 v105, v9, s77, v7
	v_and_or_b32 v104, v8, s77, v6
	v_and_or_b32 v103, v5, s77, v3
	v_and_or_b32 v102, v4, s77, v2
	ds_read_b128 v[2:5], v149
	ds_read_u16 v106, v248 offset:24816
	ds_read_u16 v111, v248 offset:25344
	ds_read_b128 v[6:9], v150
	ds_read_u16 v107, v248 offset:25872
	ds_read_u16 v113, v248 offset:26400
	ds_read_b128 v[10:13], v151
	ds_read_u16 v114, v248 offset:26928
	ds_read_u16 v115, v248 offset:27456
	ds_read_b128 v[14:17], v152
	ds_read_u16 v116, v248 offset:27984
	ds_read_u16 v117, v248 offset:28512
	s_waitcnt lgkmcnt(0)
	v_lshlrev_b32_e32 v107, 16, v107
	v_lshlrev_b32_e32 v106, 16, v106
	v_mov_b32_e32 v108, v2
	v_mov_b32_e32 v109, v6
	v_pk_add_f32 v[106:107], v[106:107], v[108:109] neg_lo:[0,1] neg_hi:[0,1]
	v_mov_b32_e32 v6, v3
	v_pk_mul_f32 v[2:3], v[6:7], v[106:107]
	v_lshlrev_b32_e32 v7, 16, v113
	v_lshlrev_b32_e32 v6, 16, v111
	v_mov_b32_e32 v106, v4
	v_mov_b32_e32 v107, v8
	v_pk_add_f32 v[6:7], v[6:7], v[106:107] neg_lo:[0,1] neg_hi:[0,1]
	v_mov_b32_e32 v8, v5
	v_pk_mul_f32 v[4:5], v[8:9], v[6:7]
	v_lshlrev_b32_e32 v7, 16, v116
	v_lshlrev_b32_e32 v6, 16, v114
	v_mov_b32_e32 v8, v10
	v_mov_b32_e32 v9, v14
	v_pk_add_f32 v[6:7], v[6:7], v[8:9] neg_lo:[0,1] neg_hi:[0,1]
	v_mov_b32_e32 v14, v11
	v_lshlrev_b32_e32 v9, 16, v117
	v_lshlrev_b32_e32 v8, 16, v115
	v_mov_b32_e32 v10, v12
	v_mov_b32_e32 v11, v16
	v_pk_add_f32 v[8:9], v[8:9], v[10:11] neg_lo:[0,1] neg_hi:[0,1]
	v_mov_b32_e32 v16, v13
	v_pk_mul_f32 v[8:9], v[16:17], v[8:9]
	v_pk_fma_f32 v[4:5], v[110:111], v[4:5], v[112:113] op_sel_hi:[0,1,0]
	v_pk_mul_f32 v[6:7], v[14:15], v[6:7]
	v_pk_fma_f32 v[8:9], v[110:111], v[8:9], v[112:113] op_sel_hi:[0,1,0]
	v_pk_fma_f32 v[2:3], v[110:111], v[2:3], v[112:113] op_sel_hi:[0,1,0]
	v_pk_fma_f32 v[6:7], v[110:111], v[6:7], v[112:113] op_sel_hi:[0,1,0]
	v_bfe_u32 v10, v9, 16, 1
	v_bfe_u32 v11, v8, 16, 1
	v_bfe_u32 v12, v5, 16, 1
	v_bfe_u32 v13, v4, 16, 1
	v_add3_u32 v4, v4, v13, s53
	v_add3_u32 v5, v5, v12, s53
	v_add3_u32 v8, v8, v11, s53
	v_add3_u32 v9, v9, v10, s53
	v_bfe_u32 v10, v2, 16, 1
	v_bfe_u32 v11, v3, 16, 1
	v_bfe_u32 v12, v6, 16, 1
	v_bfe_u32 v13, v7, 16, 1
	v_add3_u32 v7, v7, v13, s53
	v_add3_u32 v6, v6, v12, s53
	v_add3_u32 v3, v3, v11, s53
	v_add3_u32 v2, v2, v10, s53
	v_lshrrev_b32_e32 v2, 16, v2
	v_lshrrev_b32_e32 v3, 16, v3
	v_lshrrev_b32_e32 v6, 16, v6
	v_lshrrev_b32_e32 v7, 16, v7
	v_and_or_b32 v109, v9, s77, v7
	v_and_or_b32 v108, v8, s77, v6
	v_and_or_b32 v107, v5, s77, v3
	v_and_or_b32 v106, v4, s77, v2
	ds_read_b128 v[6:9], v153
	ds_read_u16 v114, v248 offset:33264
	ds_read_u16 v116, v248 offset:33792
	ds_read_b128 v[10:13], v154
	ds_read_u16 v115, v248 offset:34320
	ds_read_u16 v117, v248 offset:34848
	ds_read_b128 v[2:5], v155
	ds_read_u16 v113, v248 offset:35376
	ds_read_u16 v111, v248 offset:35904
	ds_read_b128 v[14:17], v156
	ds_read_u16 v235, v248 offset:36432
	s_waitcnt lgkmcnt(0)
	v_lshlrev_b32_e32 v115, 16, v115
	v_lshlrev_b32_e32 v114, 16, v114
	v_mov_b32_e32 v206, v6
	v_mov_b32_e32 v207, v10
	v_pk_add_f32 v[114:115], v[114:115], v[206:207] neg_lo:[0,1] neg_hi:[0,1]
	v_lshlrev_b32_e32 v117, 16, v117
	v_lshlrev_b32_e32 v116, 16, v116
	v_mov_b32_e32 v206, v8
	v_mov_b32_e32 v207, v12
	v_pk_add_f32 v[116:117], v[116:117], v[206:207] neg_lo:[0,1] neg_hi:[0,1]
	ds_read_u16 v206, v248 offset:36960
	v_mov_b32_e32 v10, v7
	v_mov_b32_e32 v12, v9
	v_pk_mul_f32 v[6:7], v[10:11], v[114:115]
	v_pk_mul_f32 v[8:9], v[12:13], v[116:117]
	v_lshlrev_b32_e32 v11, 16, v235
	v_lshlrev_b32_e32 v10, 16, v113
	v_mov_b32_e32 v12, v2
	v_mov_b32_e32 v13, v14
	v_pk_add_f32 v[10:11], v[10:11], v[12:13] neg_lo:[0,1] neg_hi:[0,1]
	v_mov_b32_e32 v14, v3
	v_pk_mul_f32 v[2:3], v[14:15], v[10:11]
	s_waitcnt lgkmcnt(0)
	v_lshlrev_b32_e32 v11, 16, v206
	v_lshlrev_b32_e32 v10, 16, v111
	v_mov_b32_e32 v12, v4
	v_mov_b32_e32 v13, v16
	v_pk_fma_f32 v[8:9], v[110:111], v[8:9], v[112:113] op_sel_hi:[0,1,0]
	v_pk_add_f32 v[10:11], v[10:11], v[12:13] neg_lo:[0,1] neg_hi:[0,1]
	v_mov_b32_e32 v16, v5
	v_pk_mul_f32 v[4:5], v[16:17], v[10:11]
	v_bfe_u32 v12, v9, 16, 1
	v_bfe_u32 v13, v8, 16, 1
	s_barrier
	s_waitcnt vmcnt(9)
	v_pk_fma_f32 v[6:7], v[110:111], v[6:7], v[112:113] op_sel_hi:[0,1,0]
	v_pk_fma_f32 v[2:3], v[110:111], v[2:3], v[112:113] op_sel_hi:[0,1,0]
	v_pk_fma_f32 v[4:5], v[110:111], v[4:5], v[112:113] op_sel_hi:[0,1,0]
	v_add3_u32 v110, v8, v13, s53
	v_add3_u32 v111, v9, v12, s53
	ds_read_b128 v[12:15], v249
	v_bfe_u32 v10, v5, 16, 1
	v_bfe_u32 v11, v4, 16, 1
	v_add3_u32 v4, v4, v11, s53
	v_add3_u32 v5, v5, v10, s53
	v_bfe_u32 v9, v7, 16, 1
	v_bfe_u32 v10, v2, 16, 1
	v_bfe_u32 v11, v3, 16, 1
	v_add3_u32 v3, v3, v11, s53
	v_add3_u32 v2, v2, v10, s53
	v_add3_u32 v206, v7, v9, s53
	v_bfe_u32 v8, v6, 16, 1
	v_lshrrev_b32_e32 v2, 16, v2
	v_lshrrev_b32_e32 v3, 16, v3
	ds_read_b128 v[114:117], v249 offset:32
	v_lshrrev_b32_e32 v206, 16, v206
	v_add3_u32 v207, v6, v8, s53
	v_and_or_b32 v113, v5, s77, v3
	v_and_or_b32 v112, v4, s77, v2
	v_and_or_b32 v111, v111, s77, v206
	ds_read_b32 v206, v157
	s_waitcnt lgkmcnt(0)
	v_mfma_f32_32x32x16_bf16 v[2:17], v[12:15], v[82:85], 0
	v_lshrrev_b32_e32 v207, 16, v207
	v_and_or_b32 v110, v110, s77, v207
	s_lshl_b32 s0, s20, 12
	s_sub_i32 s0, s17, s0
	s_ashr_i32 s1, s0, 31
	v_mfma_f32_32x32x16_bf16 v[2:17], v[114:117], v[86:89], v[2:17]
	ds_read_b128 v[114:117], v249 offset:64
	s_waitcnt lgkmcnt(0)
	v_mfma_f32_32x32x16_bf16 v[2:17], v[114:117], v[90:93], v[2:17]
	ds_read_b128 v[114:117], v249 offset:96
	s_waitcnt lgkmcnt(0)
	v_mfma_f32_32x32x16_bf16 v[2:17], v[114:117], v[94:97], v[2:17]
	ds_read_b128 v[114:117], v249 offset:128
	s_waitcnt lgkmcnt(0)
	v_mfma_f32_32x32x16_bf16 v[2:17], v[114:117], v[98:101], v[2:17]
	ds_read_b128 v[114:117], v249 offset:160
	s_waitcnt lgkmcnt(0)
	v_mfma_f32_32x32x16_bf16 v[2:17], v[114:117], v[102:105], v[2:17]
	ds_read_b128 v[114:117], v249 offset:192
	s_waitcnt lgkmcnt(0)
	v_mfma_f32_32x32x16_bf16 v[2:17], v[114:117], v[106:109], v[2:17]
	ds_read_b128 v[114:117], v249 offset:224
	s_waitcnt lgkmcnt(0)
	v_mfma_f32_32x32x16_bf16 v[2:17], v[114:117], v[110:113], v[2:17]
	s_nop 11
	v_add_f32_e32 v2, v2, v206
	ds_write_b32 v250, v2
	ds_read_b32 v2, v158
	s_waitcnt lgkmcnt(0)
	v_add_f32_e32 v2, v3, v2
	ds_write_b32 v204, v2
	ds_read_b32 v2, v159
	s_waitcnt lgkmcnt(0)
	v_add_f32_e32 v2, v4, v2
	ds_write_b32 v204, v2 offset:144
	ds_read_b32 v2, v160
	s_waitcnt lgkmcnt(0)
	v_add_f32_e32 v2, v5, v2
	ds_write_b32 v204, v2 offset:288
	ds_read_b32 v2, v161
	s_waitcnt lgkmcnt(0)
	v_add_f32_e32 v2, v6, v2
	ds_write_b32 v204, v2 offset:1008
	ds_read_b32 v2, v162
	s_waitcnt lgkmcnt(0)
	v_add_f32_e32 v2, v7, v2
	ds_write_b32 v204, v2 offset:1152
	ds_read_b32 v2, v163
	s_waitcnt lgkmcnt(0)
	v_add_f32_e32 v2, v8, v2
	ds_write_b32 v204, v2 offset:1296
	ds_read_b32 v2, v164
	s_waitcnt lgkmcnt(0)
	v_add_f32_e32 v2, v9, v2
	ds_write_b32 v204, v2 offset:1440
	ds_read_b32 v2, v165
	s_waitcnt lgkmcnt(0)
	v_add_f32_e32 v2, v10, v2
	ds_write_b32 v204, v2 offset:2160
	ds_read_b32 v2, v166
	s_waitcnt lgkmcnt(0)
	v_add_f32_e32 v2, v11, v2
	ds_write_b32 v204, v2 offset:2304
	ds_read_b32 v2, v167
	s_waitcnt lgkmcnt(0)
	v_add_f32_e32 v2, v12, v2
	ds_write_b32 v204, v2 offset:2448
	ds_read_b32 v2, v168
	s_waitcnt lgkmcnt(0)
	v_add_f32_e32 v2, v13, v2
	ds_write_b32 v204, v2 offset:2592
	ds_read_b32 v2, v169
	s_waitcnt lgkmcnt(0)
	v_add_f32_e32 v2, v14, v2
	ds_write_b32 v204, v2 offset:3312
	ds_read_b32 v2, v170
	s_waitcnt lgkmcnt(0)
	v_add_f32_e32 v2, v15, v2
	ds_write_b32 v204, v2 offset:3456
	ds_read_b32 v2, v171
	s_waitcnt lgkmcnt(0)
	v_add_f32_e32 v2, v16, v2
	ds_write_b32 v204, v2 offset:3600
	ds_read_b32 v2, v172
	s_waitcnt lgkmcnt(0)
	v_add_f32_e32 v2, v17, v2
	ds_write_b32 v204, v2 offset:3744
	ds_read_b128 v[2:5], v249 offset:8704
	ds_read_b128 v[114:117], v249 offset:8736
	s_waitcnt lgkmcnt(0)
	v_mfma_f32_32x32x16_bf16 v[2:17], v[2:5], v[82:85], 0
	v_mfma_f32_32x32x16_bf16 v[2:17], v[114:117], v[86:89], v[2:17]
	ds_read_b128 v[114:117], v249 offset:8768
	s_waitcnt lgkmcnt(0)
	v_mfma_f32_32x32x16_bf16 v[2:17], v[114:117], v[90:93], v[2:17]
	ds_read_b128 v[114:117], v249 offset:8800
	s_waitcnt lgkmcnt(0)
	v_mfma_f32_32x32x16_bf16 v[2:17], v[114:117], v[94:97], v[2:17]
	ds_read_b128 v[114:117], v249 offset:8832
	s_waitcnt lgkmcnt(0)
	v_mfma_f32_32x32x16_bf16 v[2:17], v[114:117], v[98:101], v[2:17]
	ds_read_b128 v[114:117], v249 offset:8864
	s_waitcnt lgkmcnt(0)
	v_mfma_f32_32x32x16_bf16 v[2:17], v[114:117], v[102:105], v[2:17]
	ds_read_b128 v[114:117], v249 offset:8896
	s_waitcnt lgkmcnt(0)
	v_mfma_f32_32x32x16_bf16 v[2:17], v[114:117], v[106:109], v[2:17]
	ds_read_b128 v[114:117], v249 offset:8928
	ds_read_b32 v206, v173
	s_waitcnt lgkmcnt(0)
	v_mfma_f32_32x32x16_bf16 v[2:17], v[114:117], v[110:113], v[2:17]
	s_nop 11
	v_add_f32_e32 v2, v2, v206
	ds_write_b32 v204, v2 offset:4464
	ds_read_b32 v2, v174
	s_waitcnt lgkmcnt(0)
	v_add_f32_e32 v2, v3, v2
	ds_write_b32 v204, v2 offset:4608
	ds_read_b32 v2, v175
	s_waitcnt lgkmcnt(0)
	v_add_f32_e32 v2, v4, v2
	ds_write_b32 v204, v2 offset:4752
	ds_read_b32 v2, v176
	s_waitcnt lgkmcnt(0)
	v_add_f32_e32 v2, v5, v2
	ds_write_b32 v204, v2 offset:4896
	ds_read_b32 v2, v177
	s_waitcnt lgkmcnt(0)
	v_add_f32_e32 v2, v6, v2
	ds_write_b32 v204, v2 offset:5616
	ds_read_b32 v2, v178
	s_waitcnt lgkmcnt(0)
	v_add_f32_e32 v2, v7, v2
	ds_write_b32 v204, v2 offset:5760
	ds_read_b32 v2, v179
	s_waitcnt lgkmcnt(0)
	v_add_f32_e32 v2, v8, v2
	ds_write_b32 v204, v2 offset:5904
	ds_read_b32 v2, v180
	s_waitcnt lgkmcnt(0)
	v_add_f32_e32 v2, v9, v2
	ds_write_b32 v204, v2 offset:6048
	ds_read_b32 v2, v181
	s_waitcnt lgkmcnt(0)
	v_add_f32_e32 v2, v10, v2
	ds_write_b32 v204, v2 offset:6768
	ds_read_b32 v2, v182
	v_lshlrev_b32_e32 v10, 16, v78
	s_waitcnt lgkmcnt(0)
	v_add_f32_e32 v2, v11, v2
	ds_write_b32 v204, v2 offset:6912
	ds_read_b32 v2, v183
	v_lshlrev_b32_e32 v11, 16, v79
	s_waitcnt lgkmcnt(0)
	v_add_f32_e32 v2, v12, v2
	ds_write_b32 v204, v2 offset:7056
	ds_read_b32 v2, v184
	s_waitcnt lgkmcnt(0)
	v_add_f32_e32 v2, v13, v2
	ds_write_b32 v204, v2 offset:7200
	ds_read_b32 v2, v185
	s_waitcnt lgkmcnt(0)
	v_add_f32_e32 v2, v14, v2
	ds_write_b32 v204, v2 offset:7920
	ds_read_b32 v3, v186
	v_lshl_or_b32 v2, s20, 7, v128
	s_waitcnt lgkmcnt(0)
	v_add_f32_e32 v3, v15, v3
	ds_write_b32 v204, v3 offset:8064
	ds_read_b32 v4, v187
	v_ashrrev_i32_e32 v3, 31, v2
	v_lshlrev_b64 v[2:3], 13, v[2:3]
	v_lshl_add_u64 v[2:3], s[78:79], 0, v[2:3]
	v_lshl_add_u64 v[2:3], s[0:1], 1, v[2:3]
	s_waitcnt lgkmcnt(0)
	v_add_f32_e32 v4, v16, v4
	ds_write_b32 v204, v4 offset:8208
	ds_read_b32 v4, v188
	v_lshl_add_u64 v[6:7], s[4:5], 1, v[2:3]
	v_lshl_add_u64 v[114:115], v[6:7], 0, v[202:203]
	s_mov_b32 s0, 0x60000
	s_waitcnt lgkmcnt(0)
	v_add_f32_e32 v2, v17, v4
	ds_write_b32 v204, v2 offset:8352
	s_waitcnt lgkmcnt(0)
	ds_read_b128 v[2:5], v205
	ds_read_b128 v[6:9], v205 offset:16
	s_waitcnt lgkmcnt(0)
	v_mov_b32_e32 v12, v2
	v_mov_b32_e32 v13, v4
	v_pk_mul_f32 v[10:11], v[12:13], v[10:11]
	v_and_b32_e32 v13, 0xffff0000, v79
	v_and_b32_e32 v12, 0xffff0000, v78
	v_mov_b32_e32 v4, v3
	v_pk_mul_f32 v[2:3], v[4:5], v[12:13]
	v_lshlrev_b32_e32 v5, 16, v81
	v_lshlrev_b32_e32 v4, 16, v80
	v_mov_b32_e32 v12, v6
	v_mov_b32_e32 v13, v8
	v_pk_mul_f32 v[4:5], v[12:13], v[4:5]
	v_and_b32_e32 v13, 0xffff0000, v81
	v_and_b32_e32 v12, 0xffff0000, v80
	v_mov_b32_e32 v8, v7
	v_pk_mul_f32 v[6:7], v[8:9], v[12:13]
	v_bfe_u32 v12, v3, 16, 1
	v_bfe_u32 v8, v7, 16, 1
	v_bfe_u32 v9, v6, 16, 1
	v_bfe_u32 v13, v2, 16, 1
	v_add3_u32 v2, v2, v13, s53
	v_add3_u32 v3, v3, v12, s53
	v_add3_u32 v6, v6, v9, s53
	v_add3_u32 v7, v7, v8, s53
	v_bfe_u32 v8, v10, 16, 1
	v_bfe_u32 v9, v11, 16, 1
	v_bfe_u32 v12, v4, 16, 1
	v_bfe_u32 v13, v5, 16, 1
	v_add3_u32 v5, v5, v13, s53
	v_add3_u32 v4, v4, v12, s53
	v_add3_u32 v9, v11, v9, s53
	v_add3_u32 v8, v10, v8, s53
	v_lshrrev_b32_e32 v8, 16, v8
	v_lshrrev_b32_e32 v9, 16, v9
	v_lshrrev_b32_e32 v4, 16, v4
	v_lshrrev_b32_e32 v5, 16, v5
	v_and_or_b32 v5, v7, s77, v5
	v_and_or_b32 v4, v6, s77, v4
	v_and_or_b32 v3, v3, s77, v9
	v_and_or_b32 v2, v2, s77, v8
	ds_read_b128 v[6:9], v205 offset:2304
	global_store_dwordx4 v[114:115], v[2:5], off
	ds_read_b128 v[2:5], v205 offset:2320
	v_lshlrev_b32_e32 v11, 16, v75
	v_lshlrev_b32_e32 v10, 16, v74
	s_waitcnt lgkmcnt(0)
	v_mov_b32_e32 v12, v6
	v_mov_b32_e32 v13, v8
	v_pk_mul_f32 v[10:11], v[12:13], v[10:11]
	v_and_b32_e32 v13, 0xffff0000, v75
	v_and_b32_e32 v12, 0xffff0000, v74
	v_mov_b32_e32 v8, v7
	v_pk_mul_f32 v[6:7], v[8:9], v[12:13]
	v_lshlrev_b32_e32 v9, 16, v77
	v_lshlrev_b32_e32 v8, 16, v76
	v_mov_b32_e32 v12, v2
	v_mov_b32_e32 v13, v4
	v_pk_mul_f32 v[8:9], v[12:13], v[8:9]
	v_and_b32_e32 v13, 0xffff0000, v77
	v_and_b32_e32 v12, 0xffff0000, v76
	v_mov_b32_e32 v4, v3
	v_pk_mul_f32 v[2:3], v[4:5], v[12:13]
	v_bfe_u32 v12, v7, 16, 1
	v_bfe_u32 v4, v3, 16, 1
	v_bfe_u32 v5, v2, 16, 1
	v_bfe_u32 v13, v6, 16, 1
	v_add3_u32 v6, v6, v13, s53
	v_add3_u32 v7, v7, v12, s53
	v_add3_u32 v2, v2, v5, s53
	v_add3_u32 v3, v3, v4, s53
	v_bfe_u32 v4, v10, 16, 1
	v_bfe_u32 v5, v11, 16, 1
	v_bfe_u32 v12, v8, 16, 1
	v_bfe_u32 v13, v9, 16, 1
	v_add3_u32 v9, v9, v13, s53
	v_add3_u32 v8, v8, v12, s53
	v_add3_u32 v5, v11, v5, s53
	v_add3_u32 v4, v10, v4, s53
	v_lshrrev_b32_e32 v10, 16, v4
	v_lshrrev_b32_e32 v11, 16, v5
	v_lshrrev_b32_e32 v4, 16, v8
	v_lshrrev_b32_e32 v5, 16, v9
	v_and_or_b32 v5, v3, s77, v5
	v_and_or_b32 v4, v2, s77, v4
	v_and_or_b32 v3, v7, s77, v11
	v_and_or_b32 v2, v6, s77, v10
	v_add_co_u32_e32 v10, vcc, s57, v114
	ds_read_b128 v[6:9], v205 offset:4608
	s_nop 0
	v_addc_co_u32_e32 v11, vcc, 0, v115, vcc
	global_store_dwordx4 v[10:11], v[2:5], off
	ds_read_b128 v[2:5], v205 offset:4624
	v_lshlrev_b32_e32 v11, 16, v71
	v_lshlrev_b32_e32 v10, 16, v70
	s_waitcnt lgkmcnt(0)
	v_mov_b32_e32 v12, v6
	v_mov_b32_e32 v13, v8
	v_pk_mul_f32 v[10:11], v[12:13], v[10:11]
	v_and_b32_e32 v13, 0xffff0000, v71
	v_and_b32_e32 v12, 0xffff0000, v70
	v_mov_b32_e32 v8, v7
	v_pk_mul_f32 v[6:7], v[8:9], v[12:13]
	v_lshlrev_b32_e32 v9, 16, v73
	v_lshlrev_b32_e32 v8, 16, v72
	v_mov_b32_e32 v12, v2
	v_mov_b32_e32 v13, v4
	v_pk_mul_f32 v[8:9], v[12:13], v[8:9]
	v_and_b32_e32 v13, 0xffff0000, v73
	v_and_b32_e32 v12, 0xffff0000, v72
	v_mov_b32_e32 v4, v3
	v_pk_mul_f32 v[2:3], v[4:5], v[12:13]
	v_bfe_u32 v12, v7, 16, 1
	v_bfe_u32 v4, v3, 16, 1
	v_bfe_u32 v5, v2, 16, 1
	v_bfe_u32 v13, v6, 16, 1
	v_add3_u32 v6, v6, v13, s53
	v_add3_u32 v7, v7, v12, s53
	v_add3_u32 v2, v2, v5, s53
	v_add3_u32 v3, v3, v4, s53
	v_bfe_u32 v4, v10, 16, 1
	v_bfe_u32 v5, v11, 16, 1
	v_bfe_u32 v12, v8, 16, 1
	v_bfe_u32 v13, v9, 16, 1
	v_add3_u32 v9, v9, v13, s53
	v_add3_u32 v8, v8, v12, s53
	v_add3_u32 v5, v11, v5, s53
	v_add3_u32 v4, v10, v4, s53
	v_lshrrev_b32_e32 v10, 16, v4
	v_lshrrev_b32_e32 v11, 16, v5
	v_lshrrev_b32_e32 v4, 16, v8
	v_lshrrev_b32_e32 v5, 16, v9
	v_and_or_b32 v5, v3, s77, v5
	v_and_or_b32 v4, v2, s77, v4
	v_and_or_b32 v3, v7, s77, v11
	v_and_or_b32 v2, v6, s77, v10
	v_add_co_u32_e32 v10, vcc, s88, v114
	ds_read_b128 v[6:9], v205 offset:6912
	s_nop 0
	v_addc_co_u32_e32 v11, vcc, 0, v115, vcc
	global_store_dwordx4 v[10:11], v[2:5], off
	ds_read_b128 v[2:5], v205 offset:6928
	v_lshlrev_b32_e32 v11, 16, v67
	v_lshlrev_b32_e32 v10, 16, v66
	s_waitcnt lgkmcnt(0)
	v_mov_b32_e32 v12, v6
	v_mov_b32_e32 v13, v8
	v_pk_mul_f32 v[10:11], v[12:13], v[10:11]
	v_and_b32_e32 v13, 0xffff0000, v67
	v_and_b32_e32 v12, 0xffff0000, v66
	v_mov_b32_e32 v8, v7
	v_pk_mul_f32 v[6:7], v[8:9], v[12:13]
	v_lshlrev_b32_e32 v9, 16, v69
	v_lshlrev_b32_e32 v8, 16, v68
	v_mov_b32_e32 v12, v2
	v_mov_b32_e32 v13, v4
	v_pk_mul_f32 v[8:9], v[12:13], v[8:9]
	v_and_b32_e32 v13, 0xffff0000, v69
	v_and_b32_e32 v12, 0xffff0000, v68
	v_mov_b32_e32 v4, v3
	v_pk_mul_f32 v[2:3], v[4:5], v[12:13]
	v_bfe_u32 v12, v7, 16, 1
	v_bfe_u32 v4, v3, 16, 1
	v_bfe_u32 v5, v2, 16, 1
	v_bfe_u32 v13, v6, 16, 1
	v_add3_u32 v7, v7, v12, s53
	v_add3_u32 v3, v3, v4, s53
	v_bfe_u32 v4, v10, 16, 1
	v_bfe_u32 v12, v8, 16, 1
	v_add3_u32 v6, v6, v13, s53
	v_add3_u32 v2, v2, v5, s53
	v_bfe_u32 v5, v11, 16, 1
	v_bfe_u32 v13, v9, 16, 1
	v_add3_u32 v8, v8, v12, s53
	v_add3_u32 v4, v10, v4, s53
	v_add3_u32 v9, v9, v13, s53
	v_add3_u32 v5, v11, v5, s53
	v_lshrrev_b32_e32 v10, 16, v4
	v_lshrrev_b32_e32 v4, 16, v8
	v_lshrrev_b32_e32 v11, 16, v5
	v_lshrrev_b32_e32 v5, 16, v9
	v_and_or_b32 v4, v2, s77, v4
	v_and_or_b32 v2, v6, s77, v10
	v_add_co_u32_e32 v6, vcc, s0, v114
	v_and_or_b32 v5, v3, s77, v5
	v_and_or_b32 v3, v7, s77, v11
	v_addc_co_u32_e32 v7, vcc, 0, v115, vcc
	global_store_dwordx4 v[6:7], v[2:5], off
	s_waitcnt lgkmcnt(0)
	ds_read_b128 v[2:5], v249 offset:17408
	ds_read_b128 v[66:69], v249 offset:17440
	s_waitcnt lgkmcnt(0)
	v_mfma_f32_32x32x16_bf16 v[2:17], v[2:5], v[82:85], 0
	s_mov_b32 s0, 0x80000
	v_mfma_f32_32x32x16_bf16 v[2:17], v[66:69], v[86:89], v[2:17]
	ds_read_b128 v[66:69], v249 offset:17472
	s_waitcnt lgkmcnt(0)
	v_mfma_f32_32x32x16_bf16 v[2:17], v[66:69], v[90:93], v[2:17]
	ds_read_b128 v[66:69], v249 offset:17504
	s_waitcnt lgkmcnt(0)
	v_mfma_f32_32x32x16_bf16 v[2:17], v[66:69], v[94:97], v[2:17]
	ds_read_b128 v[66:69], v249 offset:17536
	s_waitcnt lgkmcnt(0)
	v_mfma_f32_32x32x16_bf16 v[2:17], v[66:69], v[98:101], v[2:17]
	ds_read_b128 v[66:69], v249 offset:17568
	s_waitcnt lgkmcnt(0)
	v_mfma_f32_32x32x16_bf16 v[2:17], v[66:69], v[102:105], v[2:17]
	ds_read_b128 v[66:69], v249 offset:17600
	s_waitcnt lgkmcnt(0)
	v_mfma_f32_32x32x16_bf16 v[2:17], v[66:69], v[106:109], v[2:17]
	ds_read_b128 v[66:69], v249 offset:17632
	ds_read_b32 v70, v189
	s_waitcnt lgkmcnt(0)
	v_mfma_f32_32x32x16_bf16 v[2:17], v[66:69], v[110:113], v[2:17]
	s_nop 11
	v_add_f32_e32 v2, v2, v70
	ds_write_b32 v250, v2
	ds_read_b32 v2, v190
	s_waitcnt lgkmcnt(0)
	v_add_f32_e32 v2, v3, v2
	ds_write_b32 v204, v2
	ds_read_b32 v2, v191
	s_waitcnt lgkmcnt(0)
	v_add_f32_e32 v2, v4, v2
	ds_write_b32 v204, v2 offset:144
	ds_read_b32 v2, v192
	s_waitcnt lgkmcnt(0)
	v_add_f32_e32 v2, v5, v2
	ds_write_b32 v204, v2 offset:288
	ds_read_b32 v2, v193
	s_waitcnt lgkmcnt(0)
	v_add_f32_e32 v2, v6, v2
	ds_write_b32 v204, v2 offset:1008
	ds_read_b32 v2, v194
	s_waitcnt lgkmcnt(0)
	v_add_f32_e32 v2, v7, v2
	ds_write_b32 v204, v2 offset:1152
	ds_read_b32 v2, v195
	s_waitcnt lgkmcnt(0)
	v_add_f32_e32 v2, v8, v2
	ds_write_b32 v204, v2 offset:1296
	ds_read_b32 v2, v196
	s_waitcnt lgkmcnt(0)
	v_add_f32_e32 v2, v9, v2
	ds_write_b32 v204, v2 offset:1440
	ds_read_b32 v2, v197
	s_waitcnt lgkmcnt(0)
	v_add_f32_e32 v2, v10, v2
	ds_write_b32 v204, v2 offset:2160
	ds_read_b32 v2, v198
	s_waitcnt lgkmcnt(0)
	v_add_f32_e32 v2, v11, v2
	ds_write_b32 v204, v2 offset:2304
	ds_read_b32 v2, v199
	s_waitcnt lgkmcnt(0)
	v_add_f32_e32 v2, v12, v2
	ds_write_b32 v204, v2 offset:2448
	ds_read_b32 v2, v200
	s_waitcnt lgkmcnt(0)
	v_add_f32_e32 v2, v13, v2
	ds_write_b32 v204, v2 offset:2592
	ds_read_b32 v2, v201
	s_waitcnt lgkmcnt(0)
	v_add_f32_e32 v2, v14, v2
	ds_write_b32 v204, v2 offset:3312
	ds_read_b32 v2, v208
	s_waitcnt lgkmcnt(0)
	v_add_f32_e32 v2, v15, v2
	ds_write_b32 v204, v2 offset:3456
	ds_read_b32 v2, v209
	s_waitcnt lgkmcnt(0)
	v_add_f32_e32 v2, v16, v2
	ds_write_b32 v204, v2 offset:3600
	ds_read_b32 v2, v210
	s_waitcnt lgkmcnt(0)
	v_add_f32_e32 v2, v17, v2
	ds_write_b32 v204, v2 offset:3744
	ds_read_b128 v[2:5], v249 offset:26112
	ds_read_b128 v[66:69], v249 offset:26144
	s_waitcnt lgkmcnt(0)
	v_mfma_f32_32x32x16_bf16 v[2:17], v[2:5], v[82:85], 0
	v_mfma_f32_32x32x16_bf16 v[2:17], v[66:69], v[86:89], v[2:17]
	ds_read_b128 v[66:69], v249 offset:26176
	s_waitcnt lgkmcnt(0)
	v_mfma_f32_32x32x16_bf16 v[2:17], v[66:69], v[90:93], v[2:17]
	ds_read_b128 v[66:69], v249 offset:26208
	s_waitcnt lgkmcnt(0)
	v_mfma_f32_32x32x16_bf16 v[2:17], v[66:69], v[94:97], v[2:17]
	ds_read_b128 v[66:69], v249 offset:26240
	s_waitcnt lgkmcnt(0)
	v_mfma_f32_32x32x16_bf16 v[2:17], v[66:69], v[98:101], v[2:17]
	ds_read_b128 v[66:69], v249 offset:26272
	s_waitcnt lgkmcnt(0)
	v_mfma_f32_32x32x16_bf16 v[2:17], v[66:69], v[102:105], v[2:17]
	ds_read_b128 v[66:69], v249 offset:26304
	s_waitcnt lgkmcnt(0)
	v_mfma_f32_32x32x16_bf16 v[2:17], v[66:69], v[106:109], v[2:17]
	ds_read_b128 v[66:69], v249 offset:26336
	ds_read_b32 v70, v211
	s_waitcnt lgkmcnt(0)
	v_mfma_f32_32x32x16_bf16 v[2:17], v[66:69], v[110:113], v[2:17]
	s_nop 11
	v_add_f32_e32 v2, v2, v70
	ds_write_b32 v204, v2 offset:4464
	ds_read_b32 v2, v212
	s_waitcnt lgkmcnt(0)
	v_add_f32_e32 v2, v3, v2
	ds_write_b32 v204, v2 offset:4608
	ds_read_b32 v2, v213
	s_waitcnt lgkmcnt(0)
	v_add_f32_e32 v2, v4, v2
	ds_write_b32 v204, v2 offset:4752
	ds_read_b32 v2, v214
	s_waitcnt lgkmcnt(0)
	v_add_f32_e32 v2, v5, v2
	ds_write_b32 v204, v2 offset:4896
	ds_read_b32 v2, v215
	s_waitcnt lgkmcnt(0)
	v_add_f32_e32 v2, v6, v2
	ds_write_b32 v204, v2 offset:5616
	ds_read_b32 v2, v216
	s_waitcnt lgkmcnt(0)
	v_add_f32_e32 v2, v7, v2
	ds_write_b32 v204, v2 offset:5760
	ds_read_b32 v2, v217
	s_waitcnt lgkmcnt(0)
	v_add_f32_e32 v2, v8, v2
	ds_write_b32 v204, v2 offset:5904
	ds_read_b32 v2, v218
	s_waitcnt lgkmcnt(0)
	v_add_f32_e32 v2, v9, v2
	ds_write_b32 v204, v2 offset:6048
	ds_read_b32 v2, v219
	s_waitcnt lgkmcnt(0)
	v_add_f32_e32 v2, v10, v2
	ds_write_b32 v204, v2 offset:6768
	ds_read_b32 v2, v220
	v_lshlrev_b32_e32 v10, 16, v62
	s_waitcnt lgkmcnt(0)
	v_add_f32_e32 v2, v11, v2
	ds_write_b32 v204, v2 offset:6912
	ds_read_b32 v2, v221
	v_lshlrev_b32_e32 v11, 16, v63
	s_waitcnt lgkmcnt(0)
	v_add_f32_e32 v2, v12, v2
	ds_write_b32 v204, v2 offset:7056
	ds_read_b32 v2, v222
	s_waitcnt lgkmcnt(0)
	v_add_f32_e32 v2, v13, v2
	ds_write_b32 v204, v2 offset:7200
	ds_read_b32 v2, v223
	s_waitcnt lgkmcnt(0)
	v_add_f32_e32 v2, v14, v2
	ds_write_b32 v204, v2 offset:7920
	ds_read_b32 v2, v224
	s_waitcnt lgkmcnt(0)
	v_add_f32_e32 v2, v15, v2
	ds_write_b32 v204, v2 offset:8064
	ds_read_b32 v2, v225
	s_waitcnt lgkmcnt(0)
	v_add_f32_e32 v2, v16, v2
	ds_write_b32 v204, v2 offset:8208
	ds_read_b32 v2, v226
	s_waitcnt lgkmcnt(0)
	v_add_f32_e32 v2, v17, v2
	ds_write_b32 v204, v2 offset:8352
	s_waitcnt lgkmcnt(0)
	ds_read_b128 v[2:5], v205
	ds_read_b128 v[6:9], v205 offset:16
	s_waitcnt lgkmcnt(0)
	v_mov_b32_e32 v12, v2
	v_mov_b32_e32 v13, v4
	v_pk_mul_f32 v[10:11], v[12:13], v[10:11]
	v_and_b32_e32 v13, 0xffff0000, v63
	v_and_b32_e32 v12, 0xffff0000, v62
	v_mov_b32_e32 v4, v3
	v_pk_mul_f32 v[2:3], v[4:5], v[12:13]
	v_lshlrev_b32_e32 v5, 16, v65
	v_lshlrev_b32_e32 v4, 16, v64
	v_mov_b32_e32 v12, v6
	v_mov_b32_e32 v13, v8
	v_pk_mul_f32 v[4:5], v[12:13], v[4:5]
	v_and_b32_e32 v13, 0xffff0000, v65
	v_and_b32_e32 v12, 0xffff0000, v64
	v_mov_b32_e32 v8, v7
	v_pk_mul_f32 v[6:7], v[8:9], v[12:13]
	v_bfe_u32 v12, v3, 16, 1
	v_bfe_u32 v8, v7, 16, 1
	v_bfe_u32 v9, v6, 16, 1
	v_bfe_u32 v13, v2, 16, 1
	v_add3_u32 v2, v2, v13, s53
	v_add3_u32 v3, v3, v12, s53
	v_add3_u32 v6, v6, v9, s53
	v_add3_u32 v7, v7, v8, s53
	v_bfe_u32 v8, v10, 16, 1
	v_bfe_u32 v9, v11, 16, 1
	v_bfe_u32 v12, v4, 16, 1
	v_bfe_u32 v13, v5, 16, 1
	v_add3_u32 v5, v5, v13, s53
	v_add3_u32 v4, v4, v12, s53
	v_add3_u32 v9, v11, v9, s53
	v_add3_u32 v8, v10, v8, s53
	v_lshrrev_b32_e32 v8, 16, v8
	v_lshrrev_b32_e32 v9, 16, v9
	v_lshrrev_b32_e32 v4, 16, v4
	v_lshrrev_b32_e32 v5, 16, v5
	v_and_or_b32 v5, v7, s77, v5
	v_and_or_b32 v4, v6, s77, v4
	v_and_or_b32 v3, v3, s77, v9
	v_and_or_b32 v2, v2, s77, v8
	v_add_co_u32_e32 v10, vcc, s0, v114
	ds_read_b128 v[6:9], v205 offset:2304
	s_nop 0
	v_addc_co_u32_e32 v11, vcc, 0, v115, vcc
	global_store_dwordx4 v[10:11], v[2:5], off
	ds_read_b128 v[2:5], v205 offset:2320
	v_lshlrev_b32_e32 v11, 16, v59
	v_lshlrev_b32_e32 v10, 16, v58
	s_waitcnt lgkmcnt(0)
	v_mov_b32_e32 v12, v6
	v_mov_b32_e32 v13, v8
	v_pk_mul_f32 v[10:11], v[12:13], v[10:11]
	v_and_b32_e32 v13, 0xffff0000, v59
	v_and_b32_e32 v12, 0xffff0000, v58
	v_mov_b32_e32 v8, v7
	v_pk_mul_f32 v[6:7], v[8:9], v[12:13]
	v_lshlrev_b32_e32 v9, 16, v61
	v_lshlrev_b32_e32 v8, 16, v60
	v_mov_b32_e32 v12, v2
	v_mov_b32_e32 v13, v4
	v_pk_mul_f32 v[8:9], v[12:13], v[8:9]
	v_and_b32_e32 v13, 0xffff0000, v61
	v_and_b32_e32 v12, 0xffff0000, v60
	v_mov_b32_e32 v4, v3
	v_pk_mul_f32 v[2:3], v[4:5], v[12:13]
	v_bfe_u32 v12, v7, 16, 1
	v_bfe_u32 v4, v3, 16, 1
	v_bfe_u32 v5, v2, 16, 1
	v_bfe_u32 v13, v6, 16, 1
	v_add3_u32 v6, v6, v13, s53
	v_add3_u32 v7, v7, v12, s53
	v_add3_u32 v2, v2, v5, s53
	v_add3_u32 v3, v3, v4, s53
	v_bfe_u32 v4, v10, 16, 1
	v_bfe_u32 v5, v11, 16, 1
	v_bfe_u32 v12, v8, 16, 1
	v_bfe_u32 v13, v9, 16, 1
	v_add3_u32 v9, v9, v13, s53
	v_add3_u32 v8, v8, v12, s53
	v_add3_u32 v5, v11, v5, s53
	v_add3_u32 v4, v10, v4, s53
	v_lshrrev_b32_e32 v10, 16, v4
	v_lshrrev_b32_e32 v11, 16, v5
	v_lshrrev_b32_e32 v4, 16, v8
	v_lshrrev_b32_e32 v5, 16, v9
	s_mov_b32 s0, 0xa0000
	v_and_or_b32 v5, v3, s77, v5
	v_and_or_b32 v4, v2, s77, v4
	v_and_or_b32 v3, v7, s77, v11
	v_and_or_b32 v2, v6, s77, v10
	v_add_co_u32_e32 v10, vcc, s0, v114
	ds_read_b128 v[6:9], v205 offset:4608
	s_nop 0
	v_addc_co_u32_e32 v11, vcc, 0, v115, vcc
	global_store_dwordx4 v[10:11], v[2:5], off
	ds_read_b128 v[2:5], v205 offset:4624
	v_lshlrev_b32_e32 v11, 16, v55
	v_lshlrev_b32_e32 v10, 16, v54
	s_waitcnt lgkmcnt(0)
	v_mov_b32_e32 v12, v6
	v_mov_b32_e32 v13, v8
	v_pk_mul_f32 v[10:11], v[12:13], v[10:11]
	v_and_b32_e32 v13, 0xffff0000, v55
	v_and_b32_e32 v12, 0xffff0000, v54
	v_mov_b32_e32 v8, v7
	v_pk_mul_f32 v[6:7], v[8:9], v[12:13]
	v_lshlrev_b32_e32 v9, 16, v57
	v_lshlrev_b32_e32 v8, 16, v56
	v_mov_b32_e32 v12, v2
	v_mov_b32_e32 v13, v4
	v_pk_mul_f32 v[8:9], v[12:13], v[8:9]
	v_and_b32_e32 v13, 0xffff0000, v57
	v_and_b32_e32 v12, 0xffff0000, v56
	v_mov_b32_e32 v4, v3
	v_pk_mul_f32 v[2:3], v[4:5], v[12:13]
	v_bfe_u32 v12, v7, 16, 1
	v_bfe_u32 v4, v3, 16, 1
	v_bfe_u32 v5, v2, 16, 1
	v_bfe_u32 v13, v6, 16, 1
	v_add3_u32 v6, v6, v13, s53
	v_add3_u32 v7, v7, v12, s53
	v_add3_u32 v2, v2, v5, s53
	v_add3_u32 v3, v3, v4, s53
	v_bfe_u32 v4, v10, 16, 1
	v_bfe_u32 v5, v11, 16, 1
	v_bfe_u32 v12, v8, 16, 1
	v_bfe_u32 v13, v9, 16, 1
	v_add3_u32 v9, v9, v13, s53
	v_add3_u32 v8, v8, v12, s53
	v_add3_u32 v5, v11, v5, s53
	v_add3_u32 v4, v10, v4, s53
	v_lshrrev_b32_e32 v10, 16, v4
	v_lshrrev_b32_e32 v11, 16, v5
	v_lshrrev_b32_e32 v4, 16, v8
	v_lshrrev_b32_e32 v5, 16, v9
	s_mov_b32 s0, 0xc0000
	v_and_or_b32 v5, v3, s77, v5
	v_and_or_b32 v4, v2, s77, v4
	v_and_or_b32 v3, v7, s77, v11
	v_and_or_b32 v2, v6, s77, v10
	v_add_co_u32_e32 v10, vcc, s0, v114
	ds_read_b128 v[6:9], v205 offset:6912
	s_nop 0
	v_addc_co_u32_e32 v11, vcc, 0, v115, vcc
	global_store_dwordx4 v[10:11], v[2:5], off
	ds_read_b128 v[2:5], v205 offset:6928
	v_lshlrev_b32_e32 v11, 16, v51
	v_lshlrev_b32_e32 v10, 16, v50
	s_waitcnt lgkmcnt(0)
	v_mov_b32_e32 v12, v6
	v_mov_b32_e32 v13, v8
	v_pk_mul_f32 v[10:11], v[12:13], v[10:11]
	v_and_b32_e32 v13, 0xffff0000, v51
	v_and_b32_e32 v12, 0xffff0000, v50
	v_mov_b32_e32 v8, v7
	v_pk_mul_f32 v[6:7], v[8:9], v[12:13]
	v_lshlrev_b32_e32 v9, 16, v53
	v_lshlrev_b32_e32 v8, 16, v52
	v_mov_b32_e32 v12, v2
	v_mov_b32_e32 v13, v4
	v_pk_mul_f32 v[8:9], v[12:13], v[8:9]
	v_and_b32_e32 v13, 0xffff0000, v53
	v_and_b32_e32 v12, 0xffff0000, v52
	v_mov_b32_e32 v4, v3
	v_pk_mul_f32 v[2:3], v[4:5], v[12:13]
	v_bfe_u32 v12, v7, 16, 1
	v_bfe_u32 v4, v3, 16, 1
	v_bfe_u32 v5, v2, 16, 1
	v_bfe_u32 v13, v6, 16, 1
	v_add3_u32 v7, v7, v12, s53
	v_add3_u32 v3, v3, v4, s53
	v_bfe_u32 v4, v10, 16, 1
	v_bfe_u32 v12, v8, 16, 1
	v_add3_u32 v6, v6, v13, s53
	v_add3_u32 v2, v2, v5, s53
	v_bfe_u32 v5, v11, 16, 1
	v_bfe_u32 v13, v9, 16, 1
	v_add3_u32 v8, v8, v12, s53
	v_add3_u32 v4, v10, v4, s53
	v_add3_u32 v9, v9, v13, s53
	v_add3_u32 v5, v11, v5, s53
	v_lshrrev_b32_e32 v10, 16, v4
	v_lshrrev_b32_e32 v4, 16, v8
	s_mov_b32 s0, 0xe0000
	v_lshrrev_b32_e32 v11, 16, v5
	v_lshrrev_b32_e32 v5, 16, v9
	v_and_or_b32 v4, v2, s77, v4
	v_and_or_b32 v2, v6, s77, v10
	v_add_co_u32_e32 v6, vcc, s0, v114
	s_add_u32 s0, s78, s8
	v_and_or_b32 v5, v3, s77, v5
	v_and_or_b32 v3, v7, s77, v11
	v_addc_co_u32_e32 v7, vcc, 0, v115, vcc
	s_addc_u32 s1, s79, s9
	global_store_dwordx4 v[6:7], v[2:5], off
	s_add_u32 s0, s0, s10
	s_waitcnt lgkmcnt(0)
	s_addc_u32 s1, s1, s11
	s_add_u32 s8, s0, 0x20000
	s_nop 4
	global_load_dwordx4 v[78:81], v130, s[0:1] nt
	s_addc_u32 s9, s1, 0
	s_nop 4
	global_load_dwordx4 v[74:77], v130, s[8:9] nt
	s_add_u32 s8, s0, 0x40000
	s_addc_u32 s9, s1, 0
	s_nop 4
	global_load_dwordx4 v[70:73], v130, s[8:9] nt
	s_add_u32 s8, s0, 0x60000
	s_addc_u32 s9, s1, 0
	s_nop 4
	global_load_dwordx4 v[66:69], v130, s[8:9] nt
	s_add_u32 s8, s0, 0x80000
	s_addc_u32 s9, s1, 0
	s_nop 4
	global_load_dwordx4 v[62:65], v130, s[8:9] nt
	s_add_u32 s8, s0, 0xa0000
	s_addc_u32 s9, s1, 0
	s_nop 4
	global_load_dwordx4 v[58:61], v130, s[8:9] nt
	s_add_u32 s8, s0, 0xc0000
	s_addc_u32 s9, s1, 0
	s_nop 4
	global_load_dwordx4 v[54:57], v130, s[8:9] nt
	s_add_u32 s0, s0, 0xe0000
	s_addc_u32 s1, s1, 0
	s_nop 4
	global_load_dwordx4 v[50:53], v130, s[0:1] nt
	s_add_i32 s17, s17, s14
	s_add_i32 s16, s16, s15
	s_and_b64 vcc, exec, s[6:7]
	s_barrier
	s_cbranch_vccz .LBB0_634
	s_mov_b32 s10, s19
	s_branch .LBB0_625
